# sparse attention: K fragments of the next block requested right behind the mid-step barrier (own registers; V^T fragments moved to the former out accumulators, which now wait in a per-wave LDS stash b
# speedup vs baseline: 1.0266x; 1.0013x over previous
.LBB0_2063:
	s_or_b64 exec, exec, s[0:1]
	s_cmpk_gt_i32 s90, 0x3ff
	v_readlane_b32 s68, v251, 50
	v_readlane_b32 s69, v251, 51
	s_waitcnt lgkmcnt(0)
	s_barrier
	s_cbranch_scc1 .LBB0_2167
	v_readlane_b32 s0, v251, 7
	v_and_b32_e32 v112, 15, v152
	v_lshrrev_b32_e32 v113, 4, v152
	s_nop 1
	s_and_b32 s34, s0, 3
	s_lshr_b32 s35, s0, 2
	v_lshrrev_b32_e32 v220, 3, v153
	v_and_b32_e32 v221, 7, v153
	v_and_b32_e32 v222, 7, v220
	v_xor_b32_e32 v222, v222, v221
	v_lshlrev_b32_e32 v222, 4, v222
	v_lshl_add_u32 v114, v220, 7, v222
	v_mul_u32_u24_e32 v123, 0x90, v220
	v_lshl_add_u32 v123, v221, 4, v123
	v_add_u32_e32 v123, 0x2400, v123
	v_mul_u32_u24_e32 v117, 0x600, v220
	v_lshl_add_u32 v117, v221, 4, v117
	v_lshlrev_b32_e32 v118, 12, v220
	v_lshl_add_u32 v118, v221, 4, v118
	v_mul_u32_u24_e32 v116, 0x90, v112
	v_lshl_add_u32 v116, v113, 3, v116
	v_and_b32_e32 v222, 7, v112
	v_xor_b32_e32 v222, v222, v113
	v_lshlrev_b32_e32 v222, 4, v222
	v_lshl_add_u32 v115, v112, 7, v222
	v_xor_b32_e32 v122, 64, v115
	s_lshl_b32 s1, s0, 13
	s_add_i32 s1, s1, 0x9000
	v_lshl_add_u32 v250, v152, 4, s1
	v_mov_b32_e32 v226, 0xf149f2ca
	v_mov_b32_e32 v227, 0xff61b1e6
	v_mov_b32_e32 v203, 0x41000000
	v_mov_b32_e32 v238, 0
	v_mov_b32_e32 v224, 0xff800000
	s_mov_b32 s26, s90
	s_mov_b32 s50, 0
.Lnsa_task:
	s_lshr_b32 s65, s26, 8
	s_and_b32 s1, s26, 255
	s_and_b32 s2, s1, 7
	s_lshr_b32 s1, s1, 3
	s_lshl_b32 s2, s2, 5
	s_or_b32 s1, s1, s2
	s_and_b32 s28, s1, 31
	s_sub_i32 s2, 31, s28
	s_bitcmp1_b32 s65, 0
	s_cselect_b32 s28, s2, s28
	s_lshr_b32 s29, s1, 5
	s_lshl_b32 s2, s65, 3
	s_add_i32 s29, s29, s2
	s_lshr_b32 s30, s29, 1
	s_and_b32 s31, s29, 1
	s_lshl_b32 s36, s31, 2
	s_add_i32 s36, s36, s34
	s_lshl_b32 s33, s28, 6
	s_mov_b32 s32, s28
	s_lshl_b32 s2, s35, 5
	s_add_i32 s2, s2, s33
	v_add_u32_e32 v86, s2, v112
	v_add_u32_e32 v87, 16, v86
	s_lshl_b32 s3, s30, 11
	v_add_u32_e32 v220, s3, v86
	v_lshlrev_b32_e32 v234, 10, v220
	s_lshl_b32 s4, s36, 7
	v_add_u32_e32 v234, s4, v234
	v_lshl_add_u32 v234, v113, 4, v234
	v_mov_b32_e32 v235, 0
	s_add_u32 s4, s96, 0xe000000
	s_addc_u32 s5, s97, 0
	v_lshl_add_u64 v[234:235], s[4:5], 0, v[234:235]
	global_load_dwordx4 v[160:163], v[234:235], off
	global_load_dwordx4 v[164:167], v[234:235], off offset:64
	v_lshlrev_b32_e32 v236, 8, v86
	v_lshl_add_u32 v236, v113, 6, v236
	s_add_u32 s4, s96, 0x2c00000
	s_addc_u32 s5, s97, 0
	global_load_dwordx4 v[124:127], v236, s[4:5] offset:0
	global_load_dwordx4 v[128:131], v236, s[4:5] offset:16
	global_load_dwordx4 v[132:135], v236, s[4:5] offset:32
	global_load_dwordx4 v[136:139], v236, s[4:5] offset:48
	s_lshl_b32 s6, s29, 11
	v_add_u32_e32 v221, s6, v86
	v_lshlrev_b32_e32 v221, 2, v221
	s_add_u32 s4, s96, 0x2e00000
	s_addc_u32 s5, s97, 0
	global_load_dword v84, v221, s[4:5]
	v_add_u32_e32 v220, s3, v87
	v_lshlrev_b32_e32 v234, 10, v220
	s_lshl_b32 s4, s36, 7
	v_add_u32_e32 v234, s4, v234
	v_lshl_add_u32 v234, v113, 4, v234
	v_mov_b32_e32 v235, 0
	s_add_u32 s4, s96, 0xe000000
	s_addc_u32 s5, s97, 0
	v_lshl_add_u64 v[234:235], s[4:5], 0, v[234:235]
	global_load_dwordx4 v[168:171], v[234:235], off
	global_load_dwordx4 v[172:175], v[234:235], off offset:64
	v_lshlrev_b32_e32 v236, 8, v87
	v_lshl_add_u32 v236, v113, 6, v236
	s_add_u32 s4, s96, 0x2c00000
	s_addc_u32 s5, s97, 0
	global_load_dwordx4 v[140:143], v236, s[4:5] offset:0
	global_load_dwordx4 v[144:147], v236, s[4:5] offset:16
	global_load_dwordx4 v[148:151], v236, s[4:5] offset:32
	global_load_dwordx4 v[154:157], v236, s[4:5] offset:48
	s_lshl_b32 s6, s29, 11
	v_add_u32_e32 v221, s6, v87
	v_lshlrev_b32_e32 v221, 2, v221
	s_add_u32 s4, s96, 0x2e00000
	s_addc_u32 s5, s97, 0
	global_load_dword v85, v221, s[4:5]
	s_lshl_b32 s3, s30, 11
	s_mul_i32 s2, s36, 6
	s_add_i32 s2, s2, 2
	s_add_u32 s8, s96, 0x13000000
	s_addc_u32 s9, s97, 0
	v_add_u32_e32 v223, s3, v86
	v_lshlrev_b32_e32 v223, 6, v223
	v_add_u32_e32 v223, s2, v223
	global_load_ushort v119, v223, s[8:9]
	global_load_ushort v158, v223, s[8:9] offset:2
	v_add_u32_e32 v223, s3, v87
	v_lshlrev_b32_e32 v223, 6, v223
	v_add_u32_e32 v223, s2, v223
	global_load_ushort v159, v223, s[8:9]
	global_load_ushort v233, v223, s[8:9] offset:2
	s_add_u32 s8, s96, 0x9000000
	s_addc_u32 s9, s97, 0
	v_add_u32_e32 v223, s3, v86
	v_lshlrev_b32_e32 v223, 10, v223
	s_lshl_b32 s2, s36, 7
	v_add_u32_e32 v223, s2, v223
	v_lshl_add_u32 v223, v113, 3, v223
	global_load_dwordx2 v[16:17], v223, s[8:9] offset:0
	global_load_dwordx2 v[20:21], v223, s[8:9] offset:32
	global_load_dwordx2 v[24:25], v223, s[8:9] offset:64
	global_load_dwordx2 v[28:29], v223, s[8:9] offset:96
	v_add_u32_e32 v223, s3, v87
	v_lshlrev_b32_e32 v223, 10, v223
	s_lshl_b32 s2, s36, 7
	v_add_u32_e32 v223, s2, v223
	v_lshl_add_u32 v223, v113, 3, v223
	global_load_dwordx2 v[32:33], v223, s[8:9] offset:0
	global_load_dwordx2 v[36:37], v223, s[8:9] offset:32
	global_load_dwordx2 v[40:41], v223, s[8:9] offset:64
	global_load_dwordx2 v[44:45], v223, s[8:9] offset:96
	s_mul_i32 s2, s30, 0x300000
	s_add_u32 s8, s96, 0x10000000
	s_addc_u32 s9, s97, 0
	s_add_u32 s8, s8, s2
	s_addc_u32 s9, s9, 0
	s_lshl_b32 s2, s31, 7
	s_add_u32 s8, s8, s2
	s_addc_u32 s9, s9, 0
	s_add_u32 s10, s8, 0x200
	s_addc_u32 s11, s9, 0
	global_load_dwordx4 v[88:91], v117, s[10:11]
	s_lshl_b32 s2, s29, 18
	s_add_u32 s10, s96, 0x1b200000
	s_addc_u32 s11, s97, 0
	s_add_u32 s10, s10, s2
	s_addc_u32 s11, s11, 0
	global_load_dwordx4 v[92:95], v118, s[10:11]
	s_add_i32 s12, s32, -8
	s_max_i32 s12, s12, 0
	s_mul_i32 s13, s12, 0x18000
	s_add_u32 s10, s8, 0x400
	s_addc_u32 s11, s9, 0
	s_add_u32 s10, s10, s13
	s_addc_u32 s11, s11, 0
	global_load_dwordx4 v[192:195], v117, s[10:11]
	s_lshl_b32 s13, s12, 7
	s_add_u32 s10, s96, 0x1ba00000
	s_addc_u32 s11, s97, 0
	s_add_u32 s10, s10, s2
	s_addc_u32 s11, s11, 0
	s_add_u32 s10, s10, s13
	s_addc_u32 s11, s11, 0
	global_load_dwordx4 v[196:199], v118, s[10:11]
	s_add_i32 s6, s6, s33
	v_add_u32_e32 v221, s6, v152
	v_lshlrev_b32_e32 v221, 2, v221
	global_load_dword v222, v221, s[4:5]
	s_waitcnt vmcnt(0)
	s_nop 1
	v_or_b32_dpp v222, v222, v222 quad_perm:[1,0,3,2] row_mask:0xf bank_mask:0xf bound_ctrl:1
	s_nop 1
	v_or_b32_dpp v222, v222, v222 quad_perm:[2,3,0,1] row_mask:0xf bank_mask:0xf bound_ctrl:1
	s_nop 1
	v_or_b32_dpp v222, v222, v222 row_ror:4 row_mask:0xf bank_mask:0xf bound_ctrl:1
	s_nop 1
	v_or_b32_dpp v222, v222, v222 row_ror:8 row_mask:0xf bank_mask:0xf bound_ctrl:1
	v_mov_b32_e32 v223, v222
	s_nop 1
	v_permlane16_swap_b32_e32 v222, v223
	v_or_b32_e32 v222, v222, v223
	v_mov_b32_e32 v223, v222
	s_nop 1
	v_permlane32_swap_b32_e32 v222, v223
	v_or_b32_e32 v222, v222, v223
	s_nop 0
	v_readfirstlane_b32 s39, v222
	s_mov_b32 s7, 0x3e38aa3b
	v_lshlrev_b32_e32 v220, 16, v160
	v_lshlrev_b32_e32 v221, 16, v164
	v_mul_f32_e32 v222, v221, v125
	v_fma_f32 v222, v220, v124, -v222
	v_mul_f32_e32 v223, v220, v125
	v_fma_f32 v223, v221, v124, v223
	v_mul_f32_e32 v240, s7, v222
	v_mul_f32_e32 v244, s7, v223
	v_and_b32_e32 v220, 0xffff0000, v160
	v_and_b32_e32 v221, 0xffff0000, v164
	v_mul_f32_e32 v222, v221, v127
	v_fma_f32 v222, v220, v126, -v222
	v_mul_f32_e32 v223, v220, v127
	v_fma_f32 v223, v221, v126, v223
	v_mul_f32_e32 v241, s7, v222
	v_mul_f32_e32 v245, s7, v223
	v_lshlrev_b32_e32 v220, 16, v161
	v_lshlrev_b32_e32 v221, 16, v165
	v_mul_f32_e32 v222, v221, v129
	v_fma_f32 v222, v220, v128, -v222
	v_mul_f32_e32 v223, v220, v129
	v_fma_f32 v223, v221, v128, v223
	v_mul_f32_e32 v242, s7, v222
	v_mul_f32_e32 v246, s7, v223
	v_and_b32_e32 v220, 0xffff0000, v161
	v_and_b32_e32 v221, 0xffff0000, v165
	v_mul_f32_e32 v222, v221, v131
	v_fma_f32 v222, v220, v130, -v222
	v_mul_f32_e32 v223, v220, v131
	v_fma_f32 v223, v221, v130, v223
	v_mul_f32_e32 v243, s7, v222
	v_mul_f32_e32 v247, s7, v223
	v_cvt_pk_bf16_f32 v0, v240, v241
	v_cvt_pk_bf16_f32 v1, v242, v243
	v_cvt_pk_bf16_f32 v4, v244, v245
	v_cvt_pk_bf16_f32 v5, v246, v247
	v_lshlrev_b32_e32 v220, 16, v162
	v_lshlrev_b32_e32 v221, 16, v166
	v_mul_f32_e32 v222, v221, v133
	v_fma_f32 v222, v220, v132, -v222
	v_mul_f32_e32 v223, v220, v133
	v_fma_f32 v223, v221, v132, v223
	v_mul_f32_e32 v240, s7, v222
	v_mul_f32_e32 v244, s7, v223
	v_and_b32_e32 v220, 0xffff0000, v162
	v_and_b32_e32 v221, 0xffff0000, v166
	v_mul_f32_e32 v222, v221, v135
	v_fma_f32 v222, v220, v134, -v222
	v_mul_f32_e32 v223, v220, v135
	v_fma_f32 v223, v221, v134, v223
	v_mul_f32_e32 v241, s7, v222
	v_mul_f32_e32 v245, s7, v223
	v_lshlrev_b32_e32 v220, 16, v163
	v_lshlrev_b32_e32 v221, 16, v167
	v_mul_f32_e32 v222, v221, v137
	v_fma_f32 v222, v220, v136, -v222
	v_mul_f32_e32 v223, v220, v137
	v_fma_f32 v223, v221, v136, v223
	v_mul_f32_e32 v242, s7, v222
	v_mul_f32_e32 v246, s7, v223
	v_and_b32_e32 v220, 0xffff0000, v163
	v_and_b32_e32 v221, 0xffff0000, v167
	v_mul_f32_e32 v222, v221, v139
	v_fma_f32 v222, v220, v138, -v222
	v_mul_f32_e32 v223, v220, v139
	v_fma_f32 v223, v221, v138, v223
	v_mul_f32_e32 v243, s7, v222
	v_mul_f32_e32 v247, s7, v223
	v_cvt_pk_bf16_f32 v2, v240, v241
	v_cvt_pk_bf16_f32 v3, v242, v243
	v_cvt_pk_bf16_f32 v6, v244, v245
	v_cvt_pk_bf16_f32 v7, v246, v247
	v_lshlrev_b32_e32 v220, 16, v168
	v_lshlrev_b32_e32 v221, 16, v172
	v_mul_f32_e32 v222, v221, v141
	v_fma_f32 v222, v220, v140, -v222
	v_mul_f32_e32 v223, v220, v141
	v_fma_f32 v223, v221, v140, v223
	v_mul_f32_e32 v240, s7, v222
	v_mul_f32_e32 v244, s7, v223
	v_and_b32_e32 v220, 0xffff0000, v168
	v_and_b32_e32 v221, 0xffff0000, v172
	v_mul_f32_e32 v222, v221, v143
	v_fma_f32 v222, v220, v142, -v222
	v_mul_f32_e32 v223, v220, v143
	v_fma_f32 v223, v221, v142, v223
	v_mul_f32_e32 v241, s7, v222
	v_mul_f32_e32 v245, s7, v223
	v_lshlrev_b32_e32 v220, 16, v169
	v_lshlrev_b32_e32 v221, 16, v173
	v_mul_f32_e32 v222, v221, v145
	v_fma_f32 v222, v220, v144, -v222
	v_mul_f32_e32 v223, v220, v145
	v_fma_f32 v223, v221, v144, v223
	v_mul_f32_e32 v242, s7, v222
	v_mul_f32_e32 v246, s7, v223
	v_and_b32_e32 v220, 0xffff0000, v169
	v_and_b32_e32 v221, 0xffff0000, v173
	v_mul_f32_e32 v222, v221, v147
	v_fma_f32 v222, v220, v146, -v222
	v_mul_f32_e32 v223, v220, v147
	v_fma_f32 v223, v221, v146, v223
	v_mul_f32_e32 v243, s7, v222
	v_mul_f32_e32 v247, s7, v223
	v_cvt_pk_bf16_f32 v8, v240, v241
	v_cvt_pk_bf16_f32 v9, v242, v243
	v_cvt_pk_bf16_f32 v12, v244, v245
	v_cvt_pk_bf16_f32 v13, v246, v247
	v_lshlrev_b32_e32 v220, 16, v170
	v_lshlrev_b32_e32 v221, 16, v174
	v_mul_f32_e32 v222, v221, v149
	v_fma_f32 v222, v220, v148, -v222
	v_mul_f32_e32 v223, v220, v149
	v_fma_f32 v223, v221, v148, v223
	v_mul_f32_e32 v240, s7, v222
	v_mul_f32_e32 v244, s7, v223
	v_and_b32_e32 v220, 0xffff0000, v170
	v_and_b32_e32 v221, 0xffff0000, v174
	v_mul_f32_e32 v222, v221, v151
	v_fma_f32 v222, v220, v150, -v222
	v_mul_f32_e32 v223, v220, v151
	v_fma_f32 v223, v221, v150, v223
	v_mul_f32_e32 v241, s7, v222
	v_mul_f32_e32 v245, s7, v223
	v_lshlrev_b32_e32 v220, 16, v171
	v_lshlrev_b32_e32 v221, 16, v175
	v_mul_f32_e32 v222, v221, v155
	v_fma_f32 v222, v220, v154, -v222
	v_mul_f32_e32 v223, v220, v155
	v_fma_f32 v223, v221, v154, v223
	v_mul_f32_e32 v242, s7, v222
	v_mul_f32_e32 v246, s7, v223
	v_and_b32_e32 v220, 0xffff0000, v171
	v_and_b32_e32 v221, 0xffff0000, v175
	v_mul_f32_e32 v222, v221, v157
	v_fma_f32 v222, v220, v156, -v222
	v_mul_f32_e32 v223, v220, v157
	v_fma_f32 v223, v221, v156, v223
	v_mul_f32_e32 v243, s7, v222
	v_mul_f32_e32 v247, s7, v223
	v_cvt_pk_bf16_f32 v10, v240, v241
	v_cvt_pk_bf16_f32 v11, v242, v243
	v_cvt_pk_bf16_f32 v14, v244, v245
	v_cvt_pk_bf16_f32 v15, v246, v247
	v_and_b32_e32 v19, 0xffff0000, v17
	v_lshlrev_b32_e32 v18, 16, v17
	v_and_b32_e32 v17, 0xffff0000, v16
	v_lshlrev_b32_e32 v16, 16, v16
	v_and_b32_e32 v23, 0xffff0000, v21
	v_lshlrev_b32_e32 v22, 16, v21
	v_and_b32_e32 v21, 0xffff0000, v20
	v_lshlrev_b32_e32 v20, 16, v20
	v_and_b32_e32 v27, 0xffff0000, v25
	v_lshlrev_b32_e32 v26, 16, v25
	v_and_b32_e32 v25, 0xffff0000, v24
	v_lshlrev_b32_e32 v24, 16, v24
	v_and_b32_e32 v31, 0xffff0000, v29
	v_lshlrev_b32_e32 v30, 16, v29
	v_and_b32_e32 v29, 0xffff0000, v28
	v_lshlrev_b32_e32 v28, 16, v28
	v_and_b32_e32 v35, 0xffff0000, v33
	v_lshlrev_b32_e32 v34, 16, v33
	v_and_b32_e32 v33, 0xffff0000, v32
	v_lshlrev_b32_e32 v32, 16, v32
	v_and_b32_e32 v39, 0xffff0000, v37
	v_lshlrev_b32_e32 v38, 16, v37
	v_and_b32_e32 v37, 0xffff0000, v36
	v_lshlrev_b32_e32 v36, 16, v36
	v_and_b32_e32 v43, 0xffff0000, v41
	v_lshlrev_b32_e32 v42, 16, v41
	v_and_b32_e32 v41, 0xffff0000, v40
	v_lshlrev_b32_e32 v40, 16, v40
	v_and_b32_e32 v47, 0xffff0000, v45
	v_lshlrev_b32_e32 v46, 16, v45
	v_and_b32_e32 v45, 0xffff0000, v44
	v_lshlrev_b32_e32 v44, 16, v44
	ds_write_b128 v250, v[16:19] offset:0
	ds_write_b128 v250, v[20:23] offset:1024
	ds_write_b128 v250, v[24:27] offset:2048
	ds_write_b128 v250, v[28:31] offset:3072
	ds_write_b128 v250, v[32:35] offset:4096
	ds_write_b128 v250, v[36:39] offset:5120
	ds_write_b128 v250, v[40:43] offset:6144
	ds_write_b128 v250, v[44:47] offset:7168
	s_waitcnt lgkmcnt(0)
	s_mov_b32 s37, 0

.Lnsa_have0_4:
	s_max_i32 s65, s41, 0
	s_mul_i32 s56, s65, 0x18000
	s_lshl_b32 s58, s65, 7
	s_add_u32 s56, s46, s56
	s_addc_u32 s57, s47, 0
	s_add_u32 s58, s48, s58
	s_addc_u32 s59, s49, 0
	global_load_dwordx4 v[96:99], v117, s[56:57]
	global_load_dwordx4 v[100:103], v118, s[58:59]
	s_max_i32 s65, s42, 0
	s_mul_i32 s56, s65, 0x18000
	s_lshl_b32 s58, s65, 7
	s_add_u32 s56, s46, s56
	s_addc_u32 s57, s47, 0
	s_add_u32 s58, s48, s58
	s_addc_u32 s59, s49, 0
	global_load_dwordx4 v[104:107], v117, s[56:57]
	global_load_dwordx4 v[108:111], v118, s[58:59]
	s_waitcnt vmcnt(4)
	v_add_u32_e32 v244, s50, v114
	v_add_u32_e32 v245, s50, v123
	ds_write_b128 v244, v[88:91]
	ds_write_b128 v245, v[92:95]
	s_ff1_i32_b32 s40, s38
	s_add_i32 s65, s38, -1
	s_and_b32 s38, s38, s65
	s_max_i32 s65, s40, 0
	s_mul_i32 s56, s65, 0x18000
	s_lshl_b32 s58, s65, 7
	s_add_u32 s56, s46, s56
	s_addc_u32 s57, s47, 0
	s_add_u32 s58, s48, s58
	s_addc_u32 s59, s49, 0
	global_load_dwordx4 v[88:91], v117, s[56:57]
	global_load_dwordx4 v[92:95], v118, s[58:59]
	s_waitcnt lgkmcnt(0)
	s_barrier
	v_add_u32_e32 v225, s50, v115
	v_add_u32_e32 v246, s50, v122
	ds_read_b128 v[160:163], v225 offset:0
	ds_read_b128 v[168:171], v225 offset:2048
	ds_read_b128 v[176:179], v225 offset:4096
	ds_read_b128 v[184:187], v225 offset:6144
	ds_read_b128 v[164:167], v246 offset:0
	ds_read_b128 v[172:175], v246 offset:2048
	ds_read_b128 v[180:183], v246 offset:4096
	ds_read_b128 v[188:191], v246 offset:6144
.Lnsa_loop_5:
	s_cmp_lt_i32 s15, 0
	s_cbranch_scc1 .Lnsa_brk_6
	s_waitcnt lgkmcnt(0)
	v_add_u32_e32 v247, s50, v116
	ds_read_b64 v[16:17], v247 offset:9216
	ds_read_b64 v[18:19], v247 offset:9248
	ds_read_b64 v[20:21], v247 offset:9280
	ds_read_b64 v[22:23], v247 offset:9312
	ds_read_b64 v[24:25], v247 offset:11520
	ds_read_b64 v[26:27], v247 offset:11552
	ds_read_b64 v[28:29], v247 offset:11584
	ds_read_b64 v[30:31], v247 offset:11616
	ds_read_b64 v[32:33], v247 offset:13824
	ds_read_b64 v[34:35], v247 offset:13856
	ds_read_b64 v[36:37], v247 offset:13888
	ds_read_b64 v[38:39], v247 offset:13920
	ds_read_b64 v[40:41], v247 offset:16128
	ds_read_b64 v[42:43], v247 offset:16160
	ds_read_b64 v[44:45], v247 offset:16192
	ds_read_b64 v[46:47], v247 offset:16224
	s_lshl_b32 s44, s15, 6
	s_lshl_b32 s65, 1, s15
	v_and_b32_e32 v220, s65, v248
	v_and_b32_e32 v221, s65, v249
	v_lshl_add_u32 v222, v113, 2, s44
	v_cmp_ne_u32_e64 s[60:61], 0, v220
	v_cmp_ne_u32_e64 s[62:63], 0, v221
	v_sub_u32_e32 v120, v86, v222
	v_sub_u32_e32 v121, v87, v222
	s_cmp_eq_u32 s15, s32
	s_cselect_b32 s64, 1, 0
	s_cmp_eq_u32 s15, s14
	s_cselect_b32 s64, 1, s64
	s_xor_b32 s17, s50, 0x4800
	v_add_u32_e32 v244, s17, v114
	v_add_u32_e32 v245, s17, v123
	v_cndmask_b32_e64 v228, v227, v80, s[60:61]
	v_cndmask_b32_e64 v229, v227, v80, s[60:61]
	v_cndmask_b32_e64 v230, v227, v80, s[60:61]
	v_cndmask_b32_e64 v231, v227, v80, s[60:61]
	v_cndmask_b32_e64 v236, v227, v81, s[62:63]
	v_cndmask_b32_e64 v237, v227, v81, s[62:63]
	v_cndmask_b32_e64 v238, v227, v81, s[62:63]
	v_cndmask_b32_e64 v239, v227, v81, s[62:63]
	v_mfma_f32_16x16x32_bf16 v[124:127], v[160:163], v[0:3], v[228:231]
	v_mfma_f32_16x16x32_bf16 v[128:131], v[168:171], v[0:3], v[228:231]
	v_mfma_f32_16x16x32_bf16 v[132:135], v[176:179], v[0:3], v[228:231]
	v_mfma_f32_16x16x32_bf16 v[136:139], v[184:187], v[0:3], v[228:231]
	v_mfma_f32_16x16x32_bf16 v[124:127], v[164:167], v[4:7], v[124:127]
	v_mfma_f32_16x16x32_bf16 v[128:131], v[172:175], v[4:7], v[128:131]
	v_mfma_f32_16x16x32_bf16 v[132:135], v[180:183], v[4:7], v[132:135]
	v_mfma_f32_16x16x32_bf16 v[136:139], v[188:191], v[4:7], v[136:139]
	s_waitcnt vmcnt(4)
	ds_write_b128 v244, v[96:99]
	ds_write_b128 v245, v[100:103]
	s_mov_b32 s16, s41
	s_ff1_i32_b32 s41, s38
	s_add_i32 s65, s38, -1
	s_and_b32 s38, s38, s65
	s_max_i32 s65, s41, 0
	s_mul_i32 s56, s65, 0x18000
	s_lshl_b32 s58, s65, 7
	s_add_u32 s56, s46, s56
	s_addc_u32 s57, s47, 0
	s_add_u32 s58, s48, s58
	s_addc_u32 s59, s49, 0
	global_load_dwordx4 v[96:99], v117, s[56:57]
	global_load_dwordx4 v[100:103], v118, s[58:59]
	s_cmp_eq_u32 s64, 0
	s_cbranch_scc1 .Lnsa_nm_7
	v_cndmask_b32_e64 v240, -1, v120, s[60:61]
	v_subrev_u32_e32 v220, 0, v240
	v_subrev_u32_e32 v221, 1, v240
	v_subrev_u32_e32 v222, 2, v240
	v_subrev_u32_e32 v223, 3, v240
	v_cmp_gt_u32_e64 s[52:53], s45, v220
	v_cmp_gt_u32_e64 s[54:55], s45, v221
	v_cmp_gt_u32_e64 s[56:57], s45, v222
	v_cmp_gt_u32_e64 s[58:59], s45, v223
	v_cndmask_b32_e64 v124, v224, v124, s[52:53]
	v_cndmask_b32_e64 v125, v224, v125, s[54:55]
	v_cndmask_b32_e64 v126, v224, v126, s[56:57]
	v_cndmask_b32_e64 v127, v224, v127, s[58:59]
	v_subrev_u32_e32 v220, 16, v240
	v_subrev_u32_e32 v221, 17, v240
	v_subrev_u32_e32 v222, 18, v240
	v_subrev_u32_e32 v223, 19, v240
	v_cmp_gt_u32_e64 s[52:53], s45, v220
	v_cmp_gt_u32_e64 s[54:55], s45, v221
	v_cmp_gt_u32_e64 s[56:57], s45, v222
	v_cmp_gt_u32_e64 s[58:59], s45, v223
	v_cndmask_b32_e64 v128, v224, v128, s[52:53]
	v_cndmask_b32_e64 v129, v224, v129, s[54:55]
	v_cndmask_b32_e64 v130, v224, v130, s[56:57]
	v_cndmask_b32_e64 v131, v224, v131, s[58:59]
	v_subrev_u32_e32 v220, 32, v240
	v_subrev_u32_e32 v221, 33, v240
	v_subrev_u32_e32 v222, 34, v240
	v_subrev_u32_e32 v223, 35, v240
	v_cmp_gt_u32_e64 s[52:53], s45, v220
	v_cmp_gt_u32_e64 s[54:55], s45, v221
	v_cmp_gt_u32_e64 s[56:57], s45, v222
	v_cmp_gt_u32_e64 s[58:59], s45, v223
	v_cndmask_b32_e64 v132, v224, v132, s[52:53]
	v_cndmask_b32_e64 v133, v224, v133, s[54:55]
	v_cndmask_b32_e64 v134, v224, v134, s[56:57]
	v_cndmask_b32_e64 v135, v224, v135, s[58:59]
	v_subrev_u32_e32 v220, 48, v240
	v_subrev_u32_e32 v221, 49, v240
	v_subrev_u32_e32 v222, 50, v240
	v_subrev_u32_e32 v223, 51, v240
	v_cmp_gt_u32_e64 s[52:53], s45, v220
	v_cmp_gt_u32_e64 s[54:55], s45, v221
	v_cmp_gt_u32_e64 s[56:57], s45, v222
	v_cmp_gt_u32_e64 s[58:59], s45, v223
	v_cndmask_b32_e64 v136, v224, v136, s[52:53]
	v_cndmask_b32_e64 v137, v224, v137, s[54:55]
	v_cndmask_b32_e64 v138, v224, v138, s[56:57]
	v_cndmask_b32_e64 v139, v224, v139, s[58:59]

.Lnsa_rb_9:
	v_exp_f32_e32 v124, v124
	v_mfma_f32_16x16x32_bf16 v[140:143], v[164:167], v[12:15], v[140:143]
	v_exp_f32_e32 v125, v125
	v_exp_f32_e32 v126, v126
	v_exp_f32_e32 v127, v127
	v_mfma_f32_16x16x32_bf16 v[144:147], v[172:175], v[12:15], v[144:147]
	v_exp_f32_e32 v128, v128
	v_exp_f32_e32 v129, v129
	v_exp_f32_e32 v130, v130
	v_mfma_f32_16x16x32_bf16 v[148:151], v[180:183], v[12:15], v[148:151]
	v_exp_f32_e32 v131, v131
	v_exp_f32_e32 v132, v132
	v_exp_f32_e32 v133, v133
	v_mfma_f32_16x16x32_bf16 v[154:157], v[188:191], v[12:15], v[154:157]
	v_exp_f32_e32 v134, v134
	v_exp_f32_e32 v135, v135
	v_exp_f32_e32 v136, v136
	v_exp_f32_e32 v137, v137
	v_exp_f32_e32 v138, v138
	v_exp_f32_e32 v139, v139
	v_add_f32_e32 v232, v124, v125
	v_add_f32_e32 v232, v232, v126
	v_add_f32_e32 v232, v232, v127
	v_add_f32_e32 v232, v232, v128
	v_add_f32_e32 v232, v232, v129
	v_add_f32_e32 v232, v232, v130
	v_add_f32_e32 v232, v232, v131
	v_add_f32_e32 v232, v232, v132
	v_add_f32_e32 v232, v232, v133
	v_add_f32_e32 v232, v232, v134
	v_add_f32_e32 v232, v232, v135
	v_add_f32_e32 v232, v232, v136
	v_add_f32_e32 v232, v232, v137
	v_add_f32_e32 v232, v232, v138
	v_add_f32_e32 v232, v232, v139
	v_add_f32_e32 v82, v82, v232
	v_cvt_pk_bf16_f32 v204, v124, v125
	v_cvt_pk_bf16_f32 v205, v126, v127
	v_cvt_pk_bf16_f32 v206, v128, v129
	v_cvt_pk_bf16_f32 v207, v130, v131
	v_cvt_pk_bf16_f32 v208, v132, v133
	v_cvt_pk_bf16_f32 v209, v134, v135
	v_cvt_pk_bf16_f32 v210, v136, v137
	v_cvt_pk_bf16_f32 v211, v138, v139
	s_cmp_eq_u32 s64, 0
	s_cbranch_scc1 .Lnsa_nm_12
	v_cndmask_b32_e64 v240, -1, v121, s[62:63]
	v_subrev_u32_e32 v220, 0, v240
	v_subrev_u32_e32 v221, 1, v240
	v_subrev_u32_e32 v222, 2, v240
	v_subrev_u32_e32 v223, 3, v240
	v_cmp_gt_u32_e64 s[52:53], s45, v220
	v_cmp_gt_u32_e64 s[54:55], s45, v221
	v_cmp_gt_u32_e64 s[56:57], s45, v222
	v_cmp_gt_u32_e64 s[58:59], s45, v223
	v_cndmask_b32_e64 v140, v224, v140, s[52:53]
	v_cndmask_b32_e64 v141, v224, v141, s[54:55]
	v_cndmask_b32_e64 v142, v224, v142, s[56:57]
	v_cndmask_b32_e64 v143, v224, v143, s[58:59]
	v_subrev_u32_e32 v220, 16, v240
	v_subrev_u32_e32 v221, 17, v240
	v_subrev_u32_e32 v222, 18, v240
	v_subrev_u32_e32 v223, 19, v240
	v_cmp_gt_u32_e64 s[52:53], s45, v220
	v_cmp_gt_u32_e64 s[54:55], s45, v221
	v_cmp_gt_u32_e64 s[56:57], s45, v222
	v_cmp_gt_u32_e64 s[58:59], s45, v223
	v_cndmask_b32_e64 v144, v224, v144, s[52:53]
	v_cndmask_b32_e64 v145, v224, v145, s[54:55]
	v_cndmask_b32_e64 v146, v224, v146, s[56:57]
	v_cndmask_b32_e64 v147, v224, v147, s[58:59]
	v_subrev_u32_e32 v220, 32, v240
	v_subrev_u32_e32 v221, 33, v240
	v_subrev_u32_e32 v222, 34, v240
	v_subrev_u32_e32 v223, 35, v240
	v_cmp_gt_u32_e64 s[52:53], s45, v220
	v_cmp_gt_u32_e64 s[54:55], s45, v221
	v_cmp_gt_u32_e64 s[56:57], s45, v222
	v_cmp_gt_u32_e64 s[58:59], s45, v223
	v_cndmask_b32_e64 v148, v224, v148, s[52:53]
	v_cndmask_b32_e64 v149, v224, v149, s[54:55]
	v_cndmask_b32_e64 v150, v224, v150, s[56:57]
	v_cndmask_b32_e64 v151, v224, v151, s[58:59]
	v_subrev_u32_e32 v220, 48, v240
	v_subrev_u32_e32 v221, 49, v240
	v_subrev_u32_e32 v222, 50, v240
	v_subrev_u32_e32 v223, 51, v240
	v_cmp_gt_u32_e64 s[52:53], s45, v220
	v_cmp_gt_u32_e64 s[54:55], s45, v221
	v_cmp_gt_u32_e64 s[56:57], s45, v222
	v_cmp_gt_u32_e64 s[58:59], s45, v223
	v_cndmask_b32_e64 v154, v224, v154, s[52:53]
	v_cndmask_b32_e64 v155, v224, v155, s[54:55]
	v_cndmask_b32_e64 v156, v224, v156, s[56:57]
	v_cndmask_b32_e64 v157, v224, v157, s[58:59]

.Lnsa_rb_11:
	s_waitcnt lgkmcnt(0)
	s_barrier
	s_mov_b32 s50, s17
	s_mov_b32 s15, s16
	v_add_u32_e32 v225, s50, v115
	v_add_u32_e32 v246, s50, v122
	ds_read_b128 v[160:163], v225 offset:0
	ds_read_b128 v[168:171], v225 offset:2048
	ds_read_b128 v[176:179], v225 offset:4096
	ds_read_b128 v[184:187], v225 offset:6144
	ds_read_b128 v[164:167], v246 offset:0
	ds_read_b128 v[172:175], v246 offset:2048
	ds_read_b128 v[180:183], v246 offset:4096
	ds_read_b128 v[188:191], v246 offset:6144
	v_mfma_f32_16x16x32_bf16 v[48:51], v[16:19], v[204:207], v[48:51]
	v_exp_f32_e32 v140, v140
	v_exp_f32_e32 v141, v141
	v_exp_f32_e32 v142, v142
	v_exp_f32_e32 v143, v143
	v_mfma_f32_16x16x32_bf16 v[52:55], v[24:27], v[204:207], v[52:55]
	v_exp_f32_e32 v144, v144
	v_exp_f32_e32 v145, v145
	v_exp_f32_e32 v146, v146
	v_exp_f32_e32 v147, v147
	v_mfma_f32_16x16x32_bf16 v[56:59], v[32:35], v[204:207], v[56:59]
	v_exp_f32_e32 v148, v148
	v_exp_f32_e32 v149, v149
	v_exp_f32_e32 v150, v150
	v_exp_f32_e32 v151, v151
	v_mfma_f32_16x16x32_bf16 v[60:63], v[40:43], v[204:207], v[60:63]
	v_exp_f32_e32 v154, v154
	v_exp_f32_e32 v155, v155
	v_exp_f32_e32 v156, v156
	v_exp_f32_e32 v157, v157
	v_mfma_f32_16x16x32_bf16 v[48:51], v[20:23], v[208:211], v[48:51]
	v_add_f32_e32 v232, v140, v141
	v_add_f32_e32 v232, v232, v142
	v_add_f32_e32 v232, v232, v143
	v_add_f32_e32 v232, v232, v144
	v_mfma_f32_16x16x32_bf16 v[52:55], v[28:31], v[208:211], v[52:55]
	v_add_f32_e32 v232, v232, v145
	v_add_f32_e32 v232, v232, v146
	v_add_f32_e32 v232, v232, v147
	v_add_f32_e32 v232, v232, v148
	v_mfma_f32_16x16x32_bf16 v[56:59], v[36:39], v[208:211], v[56:59]
	v_add_f32_e32 v232, v232, v149
	v_add_f32_e32 v232, v232, v150
	v_add_f32_e32 v232, v232, v151
	v_add_f32_e32 v232, v232, v154
	v_mfma_f32_16x16x32_bf16 v[60:63], v[44:47], v[208:211], v[60:63]
	v_add_f32_e32 v232, v232, v155
	v_add_f32_e32 v232, v232, v156
	v_add_f32_e32 v232, v232, v157
	v_add_f32_e32 v83, v83, v232
	v_cvt_pk_bf16_f32 v212, v140, v141
	v_cvt_pk_bf16_f32 v213, v142, v143
	v_cvt_pk_bf16_f32 v214, v144, v145
	v_cvt_pk_bf16_f32 v215, v146, v147
	v_cvt_pk_bf16_f32 v216, v148, v149
	v_cvt_pk_bf16_f32 v217, v150, v151
	v_cvt_pk_bf16_f32 v218, v154, v155
	v_cvt_pk_bf16_f32 v219, v156, v157
	v_mfma_f32_16x16x32_bf16 v[64:67], v[16:19], v[212:215], v[64:67]
	v_mfma_f32_16x16x32_bf16 v[68:71], v[24:27], v[212:215], v[68:71]
	v_mfma_f32_16x16x32_bf16 v[72:75], v[32:35], v[212:215], v[72:75]
	v_mfma_f32_16x16x32_bf16 v[76:79], v[40:43], v[212:215], v[76:79]
	v_mfma_f32_16x16x32_bf16 v[64:67], v[20:23], v[216:219], v[64:67]
	v_mfma_f32_16x16x32_bf16 v[68:71], v[28:31], v[216:219], v[68:71]
	v_mfma_f32_16x16x32_bf16 v[72:75], v[36:39], v[216:219], v[72:75]
	v_mfma_f32_16x16x32_bf16 v[76:79], v[44:47], v[216:219], v[76:79]
	s_cmp_lt_i32 s15, 0
	s_cbranch_scc1 .Lnsa_brk_6
	s_waitcnt lgkmcnt(0)
	v_add_u32_e32 v247, s50, v116
	ds_read_b64 v[16:17], v247 offset:9216
	ds_read_b64 v[18:19], v247 offset:9248
	ds_read_b64 v[20:21], v247 offset:9280
	ds_read_b64 v[22:23], v247 offset:9312
	ds_read_b64 v[24:25], v247 offset:11520
	ds_read_b64 v[26:27], v247 offset:11552
	ds_read_b64 v[28:29], v247 offset:11584
	ds_read_b64 v[30:31], v247 offset:11616
	ds_read_b64 v[32:33], v247 offset:13824
	ds_read_b64 v[34:35], v247 offset:13856
	ds_read_b64 v[36:37], v247 offset:13888
	ds_read_b64 v[38:39], v247 offset:13920
	ds_read_b64 v[40:41], v247 offset:16128
	ds_read_b64 v[42:43], v247 offset:16160
	ds_read_b64 v[44:45], v247 offset:16192
	ds_read_b64 v[46:47], v247 offset:16224
	s_lshl_b32 s44, s15, 6
	s_lshl_b32 s65, 1, s15
	v_and_b32_e32 v220, s65, v248
	v_and_b32_e32 v221, s65, v249
	v_lshl_add_u32 v222, v113, 2, s44
	v_cmp_ne_u32_e64 s[60:61], 0, v220
	v_cmp_ne_u32_e64 s[62:63], 0, v221
	v_sub_u32_e32 v120, v86, v222
	v_sub_u32_e32 v121, v87, v222
	s_cmp_eq_u32 s15, s32
	s_cselect_b32 s64, 1, 0
	s_cmp_eq_u32 s15, s14
	s_cselect_b32 s64, 1, s64
	s_xor_b32 s17, s50, 0x4800
	v_add_u32_e32 v244, s17, v114
	v_add_u32_e32 v245, s17, v123
	v_cndmask_b32_e64 v228, v227, v80, s[60:61]
	v_cndmask_b32_e64 v229, v227, v80, s[60:61]
	v_cndmask_b32_e64 v230, v227, v80, s[60:61]
	v_cndmask_b32_e64 v231, v227, v80, s[60:61]
	v_cndmask_b32_e64 v236, v227, v81, s[62:63]
	v_cndmask_b32_e64 v237, v227, v81, s[62:63]
	v_cndmask_b32_e64 v238, v227, v81, s[62:63]
	v_cndmask_b32_e64 v239, v227, v81, s[62:63]
	v_mfma_f32_16x16x32_bf16 v[124:127], v[160:163], v[0:3], v[228:231]
	v_mfma_f32_16x16x32_bf16 v[128:131], v[168:171], v[0:3], v[228:231]
	v_mfma_f32_16x16x32_bf16 v[132:135], v[176:179], v[0:3], v[228:231]
	v_mfma_f32_16x16x32_bf16 v[136:139], v[184:187], v[0:3], v[228:231]
	v_mfma_f32_16x16x32_bf16 v[124:127], v[164:167], v[4:7], v[124:127]
	v_mfma_f32_16x16x32_bf16 v[128:131], v[172:175], v[4:7], v[128:131]
	v_mfma_f32_16x16x32_bf16 v[132:135], v[180:183], v[4:7], v[132:135]
	v_mfma_f32_16x16x32_bf16 v[136:139], v[188:191], v[4:7], v[136:139]
	s_waitcnt vmcnt(4)
	ds_write_b128 v244, v[104:107]
	ds_write_b128 v245, v[108:111]
	s_mov_b32 s16, s42
	s_ff1_i32_b32 s42, s38
	s_add_i32 s65, s38, -1
	s_and_b32 s38, s38, s65
	s_max_i32 s65, s42, 0
	s_mul_i32 s56, s65, 0x18000
	s_lshl_b32 s58, s65, 7
	s_add_u32 s56, s46, s56
	s_addc_u32 s57, s47, 0
	s_add_u32 s58, s48, s58
	s_addc_u32 s59, s49, 0
	global_load_dwordx4 v[104:107], v117, s[56:57]
	global_load_dwordx4 v[108:111], v118, s[58:59]
	s_cmp_eq_u32 s64, 0
	s_cbranch_scc1 .Lnsa_nm_13
	v_cndmask_b32_e64 v240, -1, v120, s[60:61]
	v_subrev_u32_e32 v220, 0, v240
	v_subrev_u32_e32 v221, 1, v240
	v_subrev_u32_e32 v222, 2, v240
	v_subrev_u32_e32 v223, 3, v240
	v_cmp_gt_u32_e64 s[52:53], s45, v220
	v_cmp_gt_u32_e64 s[54:55], s45, v221
	v_cmp_gt_u32_e64 s[56:57], s45, v222
	v_cmp_gt_u32_e64 s[58:59], s45, v223
	v_cndmask_b32_e64 v124, v224, v124, s[52:53]
	v_cndmask_b32_e64 v125, v224, v125, s[54:55]
	v_cndmask_b32_e64 v126, v224, v126, s[56:57]
	v_cndmask_b32_e64 v127, v224, v127, s[58:59]
	v_subrev_u32_e32 v220, 16, v240
	v_subrev_u32_e32 v221, 17, v240
	v_subrev_u32_e32 v222, 18, v240
	v_subrev_u32_e32 v223, 19, v240
	v_cmp_gt_u32_e64 s[52:53], s45, v220
	v_cmp_gt_u32_e64 s[54:55], s45, v221
	v_cmp_gt_u32_e64 s[56:57], s45, v222
	v_cmp_gt_u32_e64 s[58:59], s45, v223
	v_cndmask_b32_e64 v128, v224, v128, s[52:53]
	v_cndmask_b32_e64 v129, v224, v129, s[54:55]
	v_cndmask_b32_e64 v130, v224, v130, s[56:57]
	v_cndmask_b32_e64 v131, v224, v131, s[58:59]
	v_subrev_u32_e32 v220, 32, v240
	v_subrev_u32_e32 v221, 33, v240
	v_subrev_u32_e32 v222, 34, v240
	v_subrev_u32_e32 v223, 35, v240
	v_cmp_gt_u32_e64 s[52:53], s45, v220
	v_cmp_gt_u32_e64 s[54:55], s45, v221
	v_cmp_gt_u32_e64 s[56:57], s45, v222
	v_cmp_gt_u32_e64 s[58:59], s45, v223
	v_cndmask_b32_e64 v132, v224, v132, s[52:53]
	v_cndmask_b32_e64 v133, v224, v133, s[54:55]
	v_cndmask_b32_e64 v134, v224, v134, s[56:57]
	v_cndmask_b32_e64 v135, v224, v135, s[58:59]
	v_subrev_u32_e32 v220, 48, v240
	v_subrev_u32_e32 v221, 49, v240
	v_subrev_u32_e32 v222, 50, v240
	v_subrev_u32_e32 v223, 51, v240
	v_cmp_gt_u32_e64 s[52:53], s45, v220
	v_cmp_gt_u32_e64 s[54:55], s45, v221
	v_cmp_gt_u32_e64 s[56:57], s45, v222
	v_cmp_gt_u32_e64 s[58:59], s45, v223
	v_cndmask_b32_e64 v136, v224, v136, s[52:53]
	v_cndmask_b32_e64 v137, v224, v137, s[54:55]
	v_cndmask_b32_e64 v138, v224, v138, s[56:57]
	v_cndmask_b32_e64 v139, v224, v139, s[58:59]

.Lnsa_rb_17:
	s_waitcnt lgkmcnt(0)
	s_barrier
	s_mov_b32 s50, s17
	s_mov_b32 s15, s16
	v_add_u32_e32 v225, s50, v115
	v_add_u32_e32 v246, s50, v122
	ds_read_b128 v[160:163], v225 offset:0
	ds_read_b128 v[168:171], v225 offset:2048
	ds_read_b128 v[176:179], v225 offset:4096
	ds_read_b128 v[184:187], v225 offset:6144
	ds_read_b128 v[164:167], v246 offset:0
	ds_read_b128 v[172:175], v246 offset:2048
	ds_read_b128 v[180:183], v246 offset:4096
	ds_read_b128 v[188:191], v246 offset:6144
	v_mfma_f32_16x16x32_bf16 v[48:51], v[16:19], v[204:207], v[48:51]
	v_exp_f32_e32 v140, v140
	v_exp_f32_e32 v141, v141
	v_exp_f32_e32 v142, v142
	v_exp_f32_e32 v143, v143
	v_mfma_f32_16x16x32_bf16 v[52:55], v[24:27], v[204:207], v[52:55]
	v_exp_f32_e32 v144, v144
	v_exp_f32_e32 v145, v145
	v_exp_f32_e32 v146, v146
	v_exp_f32_e32 v147, v147
	v_mfma_f32_16x16x32_bf16 v[56:59], v[32:35], v[204:207], v[56:59]
	v_exp_f32_e32 v148, v148
	v_exp_f32_e32 v149, v149
	v_exp_f32_e32 v150, v150
	v_exp_f32_e32 v151, v151
	v_mfma_f32_16x16x32_bf16 v[60:63], v[40:43], v[204:207], v[60:63]
	v_exp_f32_e32 v154, v154
	v_exp_f32_e32 v155, v155
	v_exp_f32_e32 v156, v156
	v_exp_f32_e32 v157, v157
	v_mfma_f32_16x16x32_bf16 v[48:51], v[20:23], v[208:211], v[48:51]
	v_add_f32_e32 v232, v140, v141
	v_add_f32_e32 v232, v232, v142
	v_add_f32_e32 v232, v232, v143
	v_add_f32_e32 v232, v232, v144
	v_mfma_f32_16x16x32_bf16 v[52:55], v[28:31], v[208:211], v[52:55]
	v_add_f32_e32 v232, v232, v145
	v_add_f32_e32 v232, v232, v146
	v_add_f32_e32 v232, v232, v147
	v_add_f32_e32 v232, v232, v148
	v_mfma_f32_16x16x32_bf16 v[56:59], v[36:39], v[208:211], v[56:59]
	v_add_f32_e32 v232, v232, v149
	v_add_f32_e32 v232, v232, v150
	v_add_f32_e32 v232, v232, v151
	v_add_f32_e32 v232, v232, v154
	v_mfma_f32_16x16x32_bf16 v[60:63], v[44:47], v[208:211], v[60:63]
	v_add_f32_e32 v232, v232, v155
	v_add_f32_e32 v232, v232, v156
	v_add_f32_e32 v232, v232, v157
	v_add_f32_e32 v83, v83, v232
	v_cvt_pk_bf16_f32 v212, v140, v141
	v_cvt_pk_bf16_f32 v213, v142, v143
	v_cvt_pk_bf16_f32 v214, v144, v145
	v_cvt_pk_bf16_f32 v215, v146, v147
	v_cvt_pk_bf16_f32 v216, v148, v149
	v_cvt_pk_bf16_f32 v217, v150, v151
	v_cvt_pk_bf16_f32 v218, v154, v155
	v_cvt_pk_bf16_f32 v219, v156, v157
	v_mfma_f32_16x16x32_bf16 v[64:67], v[16:19], v[212:215], v[64:67]
	v_mfma_f32_16x16x32_bf16 v[68:71], v[24:27], v[212:215], v[68:71]
	v_mfma_f32_16x16x32_bf16 v[72:75], v[32:35], v[212:215], v[72:75]
	v_mfma_f32_16x16x32_bf16 v[76:79], v[40:43], v[212:215], v[76:79]
	v_mfma_f32_16x16x32_bf16 v[64:67], v[20:23], v[216:219], v[64:67]
	v_mfma_f32_16x16x32_bf16 v[68:71], v[28:31], v[216:219], v[68:71]
	v_mfma_f32_16x16x32_bf16 v[72:75], v[36:39], v[216:219], v[72:75]
	v_mfma_f32_16x16x32_bf16 v[76:79], v[44:47], v[216:219], v[76:79]
	s_cmp_lt_i32 s15, 0
	s_cbranch_scc1 .Lnsa_brk_6
	s_waitcnt lgkmcnt(0)
	v_add_u32_e32 v247, s50, v116
	ds_read_b64 v[16:17], v247 offset:9216
	ds_read_b64 v[18:19], v247 offset:9248
	ds_read_b64 v[20:21], v247 offset:9280
	ds_read_b64 v[22:23], v247 offset:9312
	ds_read_b64 v[24:25], v247 offset:11520
	ds_read_b64 v[26:27], v247 offset:11552
	ds_read_b64 v[28:29], v247 offset:11584
	ds_read_b64 v[30:31], v247 offset:11616
	ds_read_b64 v[32:33], v247 offset:13824
	ds_read_b64 v[34:35], v247 offset:13856
	ds_read_b64 v[36:37], v247 offset:13888
	ds_read_b64 v[38:39], v247 offset:13920
	ds_read_b64 v[40:41], v247 offset:16128
	ds_read_b64 v[42:43], v247 offset:16160
	ds_read_b64 v[44:45], v247 offset:16192
	ds_read_b64 v[46:47], v247 offset:16224
	s_lshl_b32 s44, s15, 6
	s_lshl_b32 s65, 1, s15
	v_and_b32_e32 v220, s65, v248
	v_and_b32_e32 v221, s65, v249
	v_lshl_add_u32 v222, v113, 2, s44
	v_cmp_ne_u32_e64 s[60:61], 0, v220
	v_cmp_ne_u32_e64 s[62:63], 0, v221
	v_sub_u32_e32 v120, v86, v222
	v_sub_u32_e32 v121, v87, v222
	s_cmp_eq_u32 s15, s32
	s_cselect_b32 s64, 1, 0
	s_cmp_eq_u32 s15, s14
	s_cselect_b32 s64, 1, s64
	s_xor_b32 s17, s50, 0x4800
	v_add_u32_e32 v244, s17, v114
	v_add_u32_e32 v245, s17, v123
	v_cndmask_b32_e64 v228, v227, v80, s[60:61]
	v_cndmask_b32_e64 v229, v227, v80, s[60:61]
	v_cndmask_b32_e64 v230, v227, v80, s[60:61]
	v_cndmask_b32_e64 v231, v227, v80, s[60:61]
	v_cndmask_b32_e64 v236, v227, v81, s[62:63]
	v_cndmask_b32_e64 v237, v227, v81, s[62:63]
	v_cndmask_b32_e64 v238, v227, v81, s[62:63]
	v_cndmask_b32_e64 v239, v227, v81, s[62:63]
	v_mfma_f32_16x16x32_bf16 v[124:127], v[160:163], v[0:3], v[228:231]
	v_mfma_f32_16x16x32_bf16 v[128:131], v[168:171], v[0:3], v[228:231]
	v_mfma_f32_16x16x32_bf16 v[132:135], v[176:179], v[0:3], v[228:231]
	v_mfma_f32_16x16x32_bf16 v[136:139], v[184:187], v[0:3], v[228:231]
	v_mfma_f32_16x16x32_bf16 v[124:127], v[164:167], v[4:7], v[124:127]
	v_mfma_f32_16x16x32_bf16 v[128:131], v[172:175], v[4:7], v[128:131]
	v_mfma_f32_16x16x32_bf16 v[132:135], v[180:183], v[4:7], v[132:135]
	v_mfma_f32_16x16x32_bf16 v[136:139], v[188:191], v[4:7], v[136:139]
	s_waitcnt vmcnt(4)
	ds_write_b128 v244, v[88:91]
	ds_write_b128 v245, v[92:95]
	s_mov_b32 s16, s40
	s_ff1_i32_b32 s40, s38
	s_add_i32 s65, s38, -1
	s_and_b32 s38, s38, s65
	s_max_i32 s65, s40, 0
	s_mul_i32 s56, s65, 0x18000
	s_lshl_b32 s58, s65, 7
	s_add_u32 s56, s46, s56
	s_addc_u32 s57, s47, 0
	s_add_u32 s58, s48, s58
	s_addc_u32 s59, s49, 0
	global_load_dwordx4 v[88:91], v117, s[56:57]
	global_load_dwordx4 v[92:95], v118, s[58:59]
	s_cmp_eq_u32 s64, 0
	s_cbranch_scc1 .Lnsa_nm_19
	v_cndmask_b32_e64 v240, -1, v120, s[60:61]
	v_subrev_u32_e32 v220, 0, v240
	v_subrev_u32_e32 v221, 1, v240
	v_subrev_u32_e32 v222, 2, v240
	v_subrev_u32_e32 v223, 3, v240
	v_cmp_gt_u32_e64 s[52:53], s45, v220
	v_cmp_gt_u32_e64 s[54:55], s45, v221
	v_cmp_gt_u32_e64 s[56:57], s45, v222
	v_cmp_gt_u32_e64 s[58:59], s45, v223
	v_cndmask_b32_e64 v124, v224, v124, s[52:53]
	v_cndmask_b32_e64 v125, v224, v125, s[54:55]
	v_cndmask_b32_e64 v126, v224, v126, s[56:57]
	v_cndmask_b32_e64 v127, v224, v127, s[58:59]
	v_subrev_u32_e32 v220, 16, v240
	v_subrev_u32_e32 v221, 17, v240
	v_subrev_u32_e32 v222, 18, v240
	v_subrev_u32_e32 v223, 19, v240
	v_cmp_gt_u32_e64 s[52:53], s45, v220
	v_cmp_gt_u32_e64 s[54:55], s45, v221
	v_cmp_gt_u32_e64 s[56:57], s45, v222
	v_cmp_gt_u32_e64 s[58:59], s45, v223
	v_cndmask_b32_e64 v128, v224, v128, s[52:53]
	v_cndmask_b32_e64 v129, v224, v129, s[54:55]
	v_cndmask_b32_e64 v130, v224, v130, s[56:57]
	v_cndmask_b32_e64 v131, v224, v131, s[58:59]
	v_subrev_u32_e32 v220, 32, v240
	v_subrev_u32_e32 v221, 33, v240
	v_subrev_u32_e32 v222, 34, v240
	v_subrev_u32_e32 v223, 35, v240
	v_cmp_gt_u32_e64 s[52:53], s45, v220
	v_cmp_gt_u32_e64 s[54:55], s45, v221
	v_cmp_gt_u32_e64 s[56:57], s45, v222
	v_cmp_gt_u32_e64 s[58:59], s45, v223
	v_cndmask_b32_e64 v132, v224, v132, s[52:53]
	v_cndmask_b32_e64 v133, v224, v133, s[54:55]
	v_cndmask_b32_e64 v134, v224, v134, s[56:57]
	v_cndmask_b32_e64 v135, v224, v135, s[58:59]
	v_subrev_u32_e32 v220, 48, v240
	v_subrev_u32_e32 v221, 49, v240
	v_subrev_u32_e32 v222, 50, v240
	v_subrev_u32_e32 v223, 51, v240
	v_cmp_gt_u32_e64 s[52:53], s45, v220
	v_cmp_gt_u32_e64 s[54:55], s45, v221
	v_cmp_gt_u32_e64 s[56:57], s45, v222
	v_cmp_gt_u32_e64 s[58:59], s45, v223
	v_cndmask_b32_e64 v136, v224, v136, s[52:53]
	v_cndmask_b32_e64 v137, v224, v137, s[54:55]
	v_cndmask_b32_e64 v138, v224, v138, s[56:57]
	v_cndmask_b32_e64 v139, v224, v139, s[58:59]

.Lnsa_rb_23:
	s_waitcnt lgkmcnt(0)
	s_barrier
	s_mov_b32 s50, s17
	s_mov_b32 s15, s16
	v_add_u32_e32 v225, s50, v115
	v_add_u32_e32 v246, s50, v122
	ds_read_b128 v[160:163], v225 offset:0
	ds_read_b128 v[168:171], v225 offset:2048
	ds_read_b128 v[176:179], v225 offset:4096
	ds_read_b128 v[184:187], v225 offset:6144
	ds_read_b128 v[164:167], v246 offset:0
	ds_read_b128 v[172:175], v246 offset:2048
	ds_read_b128 v[180:183], v246 offset:4096
	ds_read_b128 v[188:191], v246 offset:6144
	v_mfma_f32_16x16x32_bf16 v[48:51], v[16:19], v[204:207], v[48:51]
	v_exp_f32_e32 v140, v140
	v_exp_f32_e32 v141, v141
	v_exp_f32_e32 v142, v142
	v_exp_f32_e32 v143, v143
	v_mfma_f32_16x16x32_bf16 v[52:55], v[24:27], v[204:207], v[52:55]
	v_exp_f32_e32 v144, v144
	v_exp_f32_e32 v145, v145
	v_exp_f32_e32 v146, v146
	v_exp_f32_e32 v147, v147
	v_mfma_f32_16x16x32_bf16 v[56:59], v[32:35], v[204:207], v[56:59]
	v_exp_f32_e32 v148, v148
	v_exp_f32_e32 v149, v149
	v_exp_f32_e32 v150, v150
	v_exp_f32_e32 v151, v151
	v_mfma_f32_16x16x32_bf16 v[60:63], v[40:43], v[204:207], v[60:63]
	v_exp_f32_e32 v154, v154
	v_exp_f32_e32 v155, v155
	v_exp_f32_e32 v156, v156
	v_exp_f32_e32 v157, v157
	v_mfma_f32_16x16x32_bf16 v[48:51], v[20:23], v[208:211], v[48:51]
	v_add_f32_e32 v232, v140, v141
	v_add_f32_e32 v232, v232, v142
	v_add_f32_e32 v232, v232, v143
	v_add_f32_e32 v232, v232, v144
	v_mfma_f32_16x16x32_bf16 v[52:55], v[28:31], v[208:211], v[52:55]
	v_add_f32_e32 v232, v232, v145
	v_add_f32_e32 v232, v232, v146
	v_add_f32_e32 v232, v232, v147
	v_add_f32_e32 v232, v232, v148
	v_mfma_f32_16x16x32_bf16 v[56:59], v[36:39], v[208:211], v[56:59]
	v_add_f32_e32 v232, v232, v149
	v_add_f32_e32 v232, v232, v150
	v_add_f32_e32 v232, v232, v151
	v_add_f32_e32 v232, v232, v154
	v_mfma_f32_16x16x32_bf16 v[60:63], v[44:47], v[208:211], v[60:63]
	v_add_f32_e32 v232, v232, v155
	v_add_f32_e32 v232, v232, v156
	v_add_f32_e32 v232, v232, v157
	v_add_f32_e32 v83, v83, v232
	v_cvt_pk_bf16_f32 v212, v140, v141
	v_cvt_pk_bf16_f32 v213, v142, v143
	v_cvt_pk_bf16_f32 v214, v144, v145
	v_cvt_pk_bf16_f32 v215, v146, v147
	v_cvt_pk_bf16_f32 v216, v148, v149
	v_cvt_pk_bf16_f32 v217, v150, v151
	v_cvt_pk_bf16_f32 v218, v154, v155
	v_cvt_pk_bf16_f32 v219, v156, v157
	v_mfma_f32_16x16x32_bf16 v[64:67], v[16:19], v[212:215], v[64:67]
	v_mfma_f32_16x16x32_bf16 v[68:71], v[24:27], v[212:215], v[68:71]
	v_mfma_f32_16x16x32_bf16 v[72:75], v[32:35], v[212:215], v[72:75]
	v_mfma_f32_16x16x32_bf16 v[76:79], v[40:43], v[212:215], v[76:79]
	v_mfma_f32_16x16x32_bf16 v[64:67], v[20:23], v[216:219], v[64:67]
	v_mfma_f32_16x16x32_bf16 v[68:71], v[28:31], v[216:219], v[68:71]
	v_mfma_f32_16x16x32_bf16 v[72:75], v[36:39], v[216:219], v[72:75]
	v_mfma_f32_16x16x32_bf16 v[76:79], v[44:47], v[216:219], v[76:79]
	s_branch .Lnsa_loop_5

.Lnsa_brk_6:
	s_waitcnt vmcnt(0) lgkmcnt(0)
	ds_read_b128 v[124:127], v250 offset:0
	ds_read_b128 v[128:131], v250 offset:1024
	ds_read_b128 v[132:135], v250 offset:2048
	ds_read_b128 v[136:139], v250 offset:3072
	ds_read_b128 v[140:143], v250 offset:4096
	ds_read_b128 v[144:147], v250 offset:5120
	ds_read_b128 v[148:151], v250 offset:6144
	ds_read_b128 v[154:157], v250 offset:7168
	s_nop 7
	s_lshl_b32 s3, s30, 11
	v_mov_b32_e32 v221, v82
	s_nop 1
	v_permlane16_swap_b32_e32 v82, v221
	v_add_f32_e32 v82, v82, v221
	v_mov_b32_e32 v221, v82
	s_nop 1
	v_permlane32_swap_b32_e32 v82, v221
	v_add_f32_e32 v82, v82, v221
	v_max_f32_e32 v220, 0xda24260, v82
	s_cmp_eq_u32 s37, 1
	s_cselect_b64 vcc, -1, 0
	s_nop 1
	v_cndmask_b32_e32 v222, v119, v158, vcc
	v_lshlrev_b32_e32 v222, 16, v222
	v_div_scale_f32 v240, s[52:53], v220, v220, v222
	v_rcp_f32_e32 v241, v240
	v_div_scale_f32 v242, vcc, v222, v220, v222
	v_fma_f32 v243, -v240, v241, 1.0
	v_fmac_f32_e32 v241, v243, v241
	v_mul_f32_e32 v243, v242, v241
	v_fma_f32 v244, -v240, v243, v242
	v_fmac_f32_e32 v243, v244, v241
	v_fma_f32 v240, -v240, v243, v242
	s_nop 1
	v_div_fmas_f32 v240, v240, v241, v243
	v_div_fixup_f32 v228, v240, v220, v222
	s_waitcnt lgkmcnt(0)
	v_pk_fma_f32 v[124:125], v[48:49], v[228:229], v[124:125] op_sel_hi:[1,0,1]
	v_pk_fma_f32 v[126:127], v[50:51], v[228:229], v[126:127] op_sel_hi:[1,0,1]
	v_pk_fma_f32 v[128:129], v[52:53], v[228:229], v[128:129] op_sel_hi:[1,0,1]
	v_pk_fma_f32 v[130:131], v[54:55], v[228:229], v[130:131] op_sel_hi:[1,0,1]
	v_pk_fma_f32 v[132:133], v[56:57], v[228:229], v[132:133] op_sel_hi:[1,0,1]
	v_pk_fma_f32 v[134:135], v[58:59], v[228:229], v[134:135] op_sel_hi:[1,0,1]
	v_pk_fma_f32 v[136:137], v[60:61], v[228:229], v[136:137] op_sel_hi:[1,0,1]
	v_pk_fma_f32 v[138:139], v[62:63], v[228:229], v[138:139] op_sel_hi:[1,0,1]
	ds_write_b128 v250, v[124:127] offset:0
	ds_write_b128 v250, v[128:131] offset:1024
	ds_write_b128 v250, v[132:135] offset:2048
	ds_write_b128 v250, v[136:139] offset:3072
	v_mov_b32_e32 v221, v83
	s_nop 1
	v_permlane16_swap_b32_e32 v83, v221
	v_add_f32_e32 v83, v83, v221
	v_mov_b32_e32 v221, v83
	s_nop 1
	v_permlane32_swap_b32_e32 v83, v221
	v_add_f32_e32 v83, v83, v221
	v_max_f32_e32 v220, 0xda24260, v83
	s_cmp_eq_u32 s37, 1
	s_cselect_b64 vcc, -1, 0
	s_nop 1
	v_cndmask_b32_e32 v222, v159, v233, vcc
	v_lshlrev_b32_e32 v222, 16, v222
	v_div_scale_f32 v240, s[52:53], v220, v220, v222
	v_rcp_f32_e32 v241, v240
	v_div_scale_f32 v242, vcc, v222, v220, v222
	v_fma_f32 v243, -v240, v241, 1.0
	v_fmac_f32_e32 v241, v243, v241
	v_mul_f32_e32 v243, v242, v241
	v_fma_f32 v244, -v240, v243, v242
	v_fmac_f32_e32 v243, v244, v241
	v_fma_f32 v240, -v240, v243, v242
	s_nop 1
	v_div_fmas_f32 v240, v240, v241, v243
	v_div_fixup_f32 v228, v240, v220, v222
	v_pk_fma_f32 v[140:141], v[64:65], v[228:229], v[140:141] op_sel_hi:[1,0,1]
	v_pk_fma_f32 v[142:143], v[66:67], v[228:229], v[142:143] op_sel_hi:[1,0,1]
	v_pk_fma_f32 v[144:145], v[68:69], v[228:229], v[144:145] op_sel_hi:[1,0,1]
	v_pk_fma_f32 v[146:147], v[70:71], v[228:229], v[146:147] op_sel_hi:[1,0,1]
	v_pk_fma_f32 v[148:149], v[72:73], v[228:229], v[148:149] op_sel_hi:[1,0,1]
	v_pk_fma_f32 v[150:151], v[74:75], v[228:229], v[150:151] op_sel_hi:[1,0,1]
	v_pk_fma_f32 v[154:155], v[76:77], v[228:229], v[154:155] op_sel_hi:[1,0,1]
	v_pk_fma_f32 v[156:157], v[78:79], v[228:229], v[156:157] op_sel_hi:[1,0,1]
	ds_write_b128 v250, v[140:143] offset:4096
	ds_write_b128 v250, v[144:147] offset:5120
	ds_write_b128 v250, v[148:151] offset:6144
	ds_write_b128 v250, v[154:157] offset:7168
	s_add_i32 s37, s37, 1
	s_cmp_lt_u32 s37, 2
	s_cbranch_scc1 .Lnsa_br
	s_lshl_b32 s3, s30, 11
	s_add_u32 s8, s96, 0x9000000
	s_addc_u32 s9, s97, 0
	v_add_u32_e32 v223, s3, v86
	v_lshlrev_b32_e32 v223, 10, v223
	s_lshl_b32 s2, s36, 7
	v_add_u32_e32 v223, s2, v223
	v_lshl_add_u32 v223, v113, 3, v223
	v_cvt_pk_bf16_f32 v240, v124, v125
	v_cvt_pk_bf16_f32 v241, v126, v127
	global_store_dwordx2 v223, v[240:241], s[8:9] offset:0
	v_cvt_pk_bf16_f32 v240, v128, v129
	v_cvt_pk_bf16_f32 v241, v130, v131
	global_store_dwordx2 v223, v[240:241], s[8:9] offset:32
	v_cvt_pk_bf16_f32 v240, v132, v133
	v_cvt_pk_bf16_f32 v241, v134, v135
	global_store_dwordx2 v223, v[240:241], s[8:9] offset:64
	v_cvt_pk_bf16_f32 v240, v136, v137
	v_cvt_pk_bf16_f32 v241, v138, v139
	global_store_dwordx2 v223, v[240:241], s[8:9] offset:96
	v_add_u32_e32 v223, s3, v87
	v_lshlrev_b32_e32 v223, 10, v223
	s_lshl_b32 s2, s36, 7
	v_add_u32_e32 v223, s2, v223
	v_lshl_add_u32 v223, v113, 3, v223
	v_cvt_pk_bf16_f32 v240, v140, v141
	v_cvt_pk_bf16_f32 v241, v142, v143
	global_store_dwordx2 v223, v[240:241], s[8:9] offset:0
	v_cvt_pk_bf16_f32 v240, v144, v145
	v_cvt_pk_bf16_f32 v241, v146, v147
	global_store_dwordx2 v223, v[240:241], s[8:9] offset:32
	v_cvt_pk_bf16_f32 v240, v148, v149
	v_cvt_pk_bf16_f32 v241, v150, v151
	global_store_dwordx2 v223, v[240:241], s[8:9] offset:64
	v_cvt_pk_bf16_f32 v240, v154, v155
	v_cvt_pk_bf16_f32 v241, v156, v157
	global_store_dwordx2 v223, v[240:241], s[8:9] offset:96
	s_add_i32 s26, s26, s92
	s_cmpk_lt_i32 s26, 0x400
	s_cbranch_scc1 .Lnsa_task
